# E-phase token reduction: four ds_bpermute round trips replaced by DPP quad_perm / row_half_mirror / row_mirror moves
# baseline (speedup 1.0000x reference)
.Le_nonext:
	v_and_b32_e32 v20, 64, v208
	v_xor_b32_e32 v5, 1, v208
	v_lshlrev_b32_e32 v0, 3, v24
	v_add_u32_e32 v20, 64, v20
	v_cmp_lt_i32_e32 vcc, v5, v20
	v_xor_b32_e32 v21, 2, v208
	v_xor_b32_e32 v22, 4, v208
	v_cndmask_b32_e32 v5, v208, v5, vcc
	v_lshlrev_b32_e32 v5, 2, v5
	v_cmp_lt_i32_e32 vcc, v21, v20
	v_xor_b32_e32 v23, 8, v208
	v_pk_add_f32 v[6:7], v[6:7], v[10:11]
	v_pk_add_f32 v[8:9], v[8:9], v[12:13]
	v_pk_mul_f32 v[12:13], v[6:7], v[6:7]
	v_pk_mul_f32 v[10:11], v[8:9], v[8:9]
	v_add_f32_e32 v12, v12, v13
	v_add_f32_e32 v10, v12, v10
	v_add_f32_e32 v10, v10, v11
	s_nop 1
	v_mov_b32_dpp v5, v10 quad_perm:[1,0,3,2] row_mask:0xf bank_mask:0xf
	v_cndmask_b32_e32 v21, v208, v21, vcc
	v_lshlrev_b32_e32 v25, 2, v21
	v_cmp_lt_i32_e32 vcc, v22, v20
	s_waitcnt lgkmcnt(0)
	v_add_f32_e32 v5, v10, v5
	s_nop 1
	v_mov_b32_dpp v10, v5 quad_perm:[2,3,0,1] row_mask:0xf bank_mask:0xf
	v_cndmask_b32_e32 v22, v208, v22, vcc
	v_lshlrev_b32_e32 v26, 2, v22
	v_cmp_lt_i32_e32 vcc, v23, v20
	v_lshlrev_b32_e32 v22, 16, v18
	s_waitcnt lgkmcnt(0)
	v_add_f32_e32 v5, v5, v10
	s_nop 1
	v_mov_b32_dpp v10, v5 row_half_mirror row_mask:0xf bank_mask:0xf
	v_cndmask_b32_e32 v20, v208, v23, vcc
	v_lshlrev_b32_e32 v27, 2, v20
	v_and_b32_e32 v23, 0xffff0000, v18
	v_lshlrev_b32_e32 v18, 16, v19
	s_waitcnt lgkmcnt(0)
	v_add_f32_e32 v5, v5, v10
	v_and_b32_e32 v19, 0xffff0000, v19
	s_nop 1
	v_mov_b32_dpp v26, v5 row_mirror row_mask:0xf bank_mask:0xf
	v_mul_f32_e32 v11, 0xbfb8aa3b, v22
	v_mul_f32_e32 v12, 0xbfb8aa3b, v23
	v_mul_f32_e32 v13, 0xbfb8aa3b, v18
	v_mul_f32_e32 v28, 0xbfb8aa3b, v19
	v_exp_f32_e32 v11, v11
	v_exp_f32_e32 v12, v12
	v_exp_f32_e32 v13, v13
	v_exp_f32_e32 v25, v28
	s_waitcnt lgkmcnt(0)
	v_add_f32_e32 v5, v5, v26
	v_add_f32_e32 v11, 1.0, v11
	v_add_f32_e32 v12, 1.0, v12
	v_add_f32_e32 v13, 1.0, v13
	v_add_f32_e32 v25, 1.0, v25
	v_fmamk_f32 v5, v5, 0x3c800000, v206
	v_rcp_f32_e32 v10, v11
	v_rcp_f32_e32 v11, v12
	v_rcp_f32_e32 v12, v13
	v_rcp_f32_e32 v13, v25
	v_mul_f32_e32 v25, 0x4b800000, v5
	v_cmp_gt_f32_e32 vcc, s35, v5
	v_lshlrev_b64 v[20:21], 11, v[2:3]
	v_lshl_add_u64 v[20:21], s[6:7], 0, v[20:21]
	v_cndmask_b32_e32 v5, v5, v25, vcc
	v_rsq_f32_e32 v5, v5
	v_lshl_add_u64 v[20:21], v[20:21], 0, v[0:1]
	v_pk_mul_f32 v[10:11], v[10:11], v[22:23]
	v_pk_mul_f32 v[12:13], v[12:13], v[18:19]
	v_mul_f32_e32 v0, 0x45800000, v5
	v_cndmask_b32_e32 v0, v5, v0, vcc
	v_pk_mul_f32 v[6:7], v[6:7], v[0:1] op_sel_hi:[1,0]
	v_pk_mul_f32 v[8:9], v[8:9], v[0:1] op_sel_hi:[1,0]
	v_pk_mul_f32 v[6:7], v[14:15], v[6:7]
	v_pk_mul_f32 v[8:9], v[16:17], v[8:9]
	v_pk_mul_f32 v[6:7], v[6:7], v[10:11]
	v_pk_mul_f32 v[8:9], v[8:9], v[12:13]
	v_cvt_pk_bf16_f32 v6, v6, v7
	v_cvt_pk_bf16_f32 v7, v8, v9
	v_cmp_eq_u32_e32 vcc, 0, v24
	global_store_dwordx2 v[20:21], v[6:7], off
	s_and_saveexec_b64 s[12:13], vcc
	s_cbranch_execz .Le_skipz
	v_lshlrev_b64 v[2:3], 2, v[2:3]
	v_lshl_add_u64 v[6:7], s[8:9], 0, v[2:3]
	v_lshl_add_u64 v[2:3], s[10:11], 0, v[2:3]
	global_store_dword v[6:7], v1, off
	global_store_dword v[2:3], v1, off
